# RWKV: stage 0 (token shift) of interior chunks moved entirely onto waves 4-7, which prefetch both token halves and run it during the substitution stage of waves 0-3
# speedup vs baseline: 1.0040x; 1.0014x over previous
; __device__ __forceinline__ void rwkv_chain(LAS unsigned char* lds, int cid, const bf16_t* P0, const float* mu, const float* w0, const float* w2, const float* a0, const float* a2, ...
;     ...
;     for (int cc = 0; cc < 128; ++cc) {
;         const int t0 = dir ? (127 - cc) * 32 : cc * 32;
;         { RW_IDS
;         { const int tok = tid >> 4, c4 = (tid & 15) * 4;
.LBB0_489:
	v_mov_b32_e32 v199, 0
	s_add_i32 s7, s6, 32
	s_and_b64 vcc, s[10:11], exec
	s_cselect_b32 s7, s7, s46
	s_cmp_eq_u32 s7, 0
	s_cbranch_scc1 .Lrw_s0_here
	s_cmpk_lg_i32 s7, 0xfe0
	s_cbranch_scc1 .Lrw_s0_skip

; #define LAS __attribute__((address_space(3)))
; __device__ __forceinline__ unsigned pk2(float lo, float hi) { const f32x2 v = {lo, hi}; return __builtin_bit_cast(unsigned, __builtin_convertvector(v, bf16x2_t)); }
; __device__ __forceinline__ unsigned f2bf(float f) { return pk2(f, 0.f) & 0xffffu; }
; __device__ __forceinline__ float frcp(float x) { return __builtin_amdgcn_rcpf(x); }
; __device__ __forceinline__ float sigmoidf_(float x) { return frcp(1.0f + __expf(-x)); }
; __device__ __forceinline__ void rwkv_chain(LAS unsigned char* lds, int cid, const bf16_t* P0, const float* mu, const float* w0, const float* w2, const float* a0, const float* a2, ...
;     ...
;         { const int tok = tid >> 4, c4 = (tid & 15) * 4;
; #pragma unroll
;         for (int i = 0; i < 5; ++i) {
;             const f32x4 mu4 = *(const LAS f32x4*)(cst + (5 + i) * 64 + c4);
;             const f32x4 cv = (f32x4){bflo(rc[i].x), bfhi(rc[i].x), bflo(rc[i].y), bfhi(rc[i].y)};
;             const f32x4 pv = (f32x4){bflo(rpv[i].x), bfhi(rpv[i].x), bflo(rpv[i].y), bfhi(rpv[i].y)}, nv = (f32x4){bflo(rnx[i].x), bfhi(rnx[i].x), bflo(rnx[i].y), bfhi(rnx[i].y)};
;             const f32x4 xv = cv + mu4 * ((pv + nv) * 0.5f - cv);
;             if (i == 0) *(LAS f32x4*)(rS + tok * 64 + c4) = xv;
;             else if (i == 1) *(LAS f32x4*)(kS + tok * 64 + c4) = xv;
;             else if (i == 2) *(LAS f32x4*)(vS + tok * 64 + c4) = xv;
;             else if (i == 3) { float th[4];
; #pragma unroll
;                 for (int e = 0; e < 4; ++e) { const float ex = __expf(2.f * xv[e]); th[e] = 1.f - 2.f * frcp(ex + 1.f); }
;                 u32x2 w; w.x = pk2(th[0], th[1]); w.y = pk2(th[2], th[3]); *(LAS u32x2*)(wdB + tok * 72 + c4) = w; }
;             else { u32x2 w; w.x = pk2(xv[0], xv[1]); w.y = pk2(xv[2], xv[3]); *(LAS u32x2*)(adB + tok * 72 + c4) = w; }
;         } }
;         if (dir == 0) {
;             const int tok = tid >> 4, c = tid & 15, t = t0 + tok;
;             const float cur = bf2f(gcv), prv = bf2f(gpv), nxt = bf2f(gnv);
;             const float x = cur + cst[10 * 64 + c] * (0.5f * (prv + nxt) - cur);
;             SG[((size_t)b * SEQ + t) * 128 + h * 16 + c] = (bf16_t)f2bf(sigmoidf_(x));
.Lrw_s0_body:
	v_lshlrev_b32_e32 v16, 16, v57
	v_ashrrev_i32_e32 v9, 4, v8
	v_and_b32_e32 v8, 15, v8
	v_lshl_add_u32 v25, v8, 4, 0
	v_and_b32_e32 v17, 0xffff0000, v57
	v_lshlrev_b32_e32 v20, 16, v55
	v_and_b32_e32 v21, 0xffff0000, v55
	v_lshlrev_b32_e32 v14, 16, v56
	v_and_b32_e32 v15, 0xffff0000, v56
	v_lshlrev_b32_e32 v18, 16, v54
	v_and_b32_e32 v19, 0xffff0000, v54
	v_pk_add_f32 v[16:17], v[20:21], v[16:17]
	v_lshlrev_b32_e32 v20, 16, v53
	v_and_b32_e32 v21, 0xffff0000, v53
	v_pk_add_f32 v[14:15], v[18:19], v[14:15]
	v_lshlrev_b32_e32 v18, 16, v52
	v_and_b32_e32 v19, 0xffff0000, v52
	v_xor_b32_e32 v23, 0x80000000, v21
	v_xor_b32_e32 v22, 0x80000000, v20
	v_pk_fma_f32 v[16:17], v[16:17], 0.5, v[22:23] op_sel_hi:[1,0,1]
	v_xor_b32_e32 v23, 0x80000000, v19
	v_xor_b32_e32 v22, 0x80000000, v18
	v_pk_fma_f32 v[14:15], v[14:15], 0.5, v[22:23] op_sel_hi:[1,0,1]
	v_lshl_add_u32 v27, v9, 8, v25
	v_pk_fma_f32 v[10:11], v[14:15], v[210:211], v[18:19]
	v_pk_fma_f32 v[12:13], v[16:17], v[212:213], v[20:21]
	ds_write_b128 v27, v[10:13]
	v_lshlrev_b32_e32 v16, 16, v61
	v_and_b32_e32 v17, 0xffff0000, v61
	v_lshlrev_b32_e32 v20, 16, v63
	v_and_b32_e32 v21, 0xffff0000, v63
	v_lshlrev_b32_e32 v14, 16, v60
	v_and_b32_e32 v15, 0xffff0000, v60
	v_lshlrev_b32_e32 v18, 16, v62
	v_and_b32_e32 v19, 0xffff0000, v62
	v_pk_add_f32 v[16:17], v[20:21], v[16:17]
	v_lshlrev_b32_e32 v20, 16, v59
	v_and_b32_e32 v21, 0xffff0000, v59
	v_pk_add_f32 v[14:15], v[18:19], v[14:15]
	v_lshlrev_b32_e32 v18, 16, v58
	v_and_b32_e32 v19, 0xffff0000, v58
	v_xor_b32_e32 v23, 0x80000000, v21
	v_xor_b32_e32 v22, 0x80000000, v20
	v_pk_fma_f32 v[16:17], v[16:17], 0.5, v[22:23] op_sel_hi:[1,0,1]
	v_xor_b32_e32 v23, 0x80000000, v19
	v_xor_b32_e32 v22, 0x80000000, v18
	v_pk_fma_f32 v[14:15], v[14:15], 0.5, v[22:23] op_sel_hi:[1,0,1]
	v_pk_fma_f32 v[12:13], v[16:17], v[216:217], v[20:21]
	v_pk_fma_f32 v[10:11], v[14:15], v[214:215], v[18:19]
	ds_write_b128 v27, v[10:13] offset:8192
	v_lshlrev_b32_e32 v16, 16, v67
	v_and_b32_e32 v17, 0xffff0000, v67
	v_lshlrev_b32_e32 v20, 16, v69
	v_and_b32_e32 v21, 0xffff0000, v69
	v_lshlrev_b32_e32 v14, 16, v66
	v_and_b32_e32 v15, 0xffff0000, v66
	v_lshlrev_b32_e32 v18, 16, v68
	v_and_b32_e32 v19, 0xffff0000, v68
	v_pk_add_f32 v[16:17], v[20:21], v[16:17]
	v_lshlrev_b32_e32 v20, 16, v65
	v_and_b32_e32 v21, 0xffff0000, v65
	v_pk_add_f32 v[14:15], v[18:19], v[14:15]
	v_lshlrev_b32_e32 v18, 16, v64
	v_and_b32_e32 v19, 0xffff0000, v64
	v_xor_b32_e32 v23, 0x80000000, v21
	v_xor_b32_e32 v22, 0x80000000, v20
	v_pk_fma_f32 v[16:17], v[16:17], 0.5, v[22:23] op_sel_hi:[1,0,1]
	v_xor_b32_e32 v23, 0x80000000, v19
	v_xor_b32_e32 v22, 0x80000000, v18
	v_pk_fma_f32 v[14:15], v[14:15], 0.5, v[22:23] op_sel_hi:[1,0,1]
	v_pk_fma_f32 v[12:13], v[16:17], v[220:221], v[20:21]
	v_pk_fma_f32 v[10:11], v[14:15], v[218:219], v[18:19]
	ds_write_b128 v27, v[10:13] offset:16384
	v_lshlrev_b32_e32 v14, 16, v72
	v_and_b32_e32 v15, 0xffff0000, v72
	v_lshlrev_b32_e32 v18, 16, v74
	v_and_b32_e32 v19, 0xffff0000, v74
	v_pk_add_f32 v[14:15], v[18:19], v[14:15]
	v_lshlrev_b32_e32 v18, 16, v70
	v_and_b32_e32 v19, 0xffff0000, v70
	v_xor_b32_e32 v23, 0x80000000, v19
	v_xor_b32_e32 v22, 0x80000000, v18
	v_pk_fma_f32 v[14:15], v[14:15], 0.5, v[22:23] op_sel_hi:[1,0,1]
	v_lshlrev_b32_e32 v16, 16, v73
	v_pk_fma_f32 v[10:11], v[14:15], v[222:223], v[18:19]
	v_and_b32_e32 v17, 0xffff0000, v73
	v_lshlrev_b32_e32 v20, 16, v75
	v_and_b32_e32 v21, 0xffff0000, v75
	v_add_f32_e32 v10, v10, v10
	v_pk_add_f32 v[16:17], v[20:21], v[16:17]
	v_lshlrev_b32_e32 v20, 16, v71
	v_and_b32_e32 v21, 0xffff0000, v71
	v_mul_f32_e32 v10, 0x3fb8aa3b, v10
	v_xor_b32_e32 v23, 0x80000000, v21
	v_xor_b32_e32 v22, 0x80000000, v20
	v_exp_f32_e32 v14, v10
	v_add_f32_e32 v10, v11, v11
	v_pk_fma_f32 v[16:17], v[16:17], 0.5, v[22:23] op_sel_hi:[1,0,1]
	v_mul_f32_e32 v10, 0x3fb8aa3b, v10
	v_exp_f32_e32 v15, v10
	v_pk_fma_f32 v[10:11], v[16:17], v[224:225], v[20:21]
	v_add_f32_e32 v12, 1.0, v14
	v_add_f32_e32 v10, v10, v10
	v_add_f32_e32 v11, v11, v11
	v_mul_f32_e32 v10, 0x3fb8aa3b, v10
	v_mul_f32_e32 v11, 0x3fb8aa3b, v11
	v_exp_f32_e32 v10, v10
	v_exp_f32_e32 v11, v11
	v_add_f32_e32 v13, 1.0, v15
	v_rcp_f32_e32 v12, v12
	v_add_f32_e32 v10, 1.0, v10
	v_add_f32_e32 v11, 1.0, v11
	v_rcp_f32_e32 v13, v13
	v_rcp_f32_e32 v10, v10
	v_rcp_f32_e32 v11, v11
	v_lshlrev_b32_e32 v24, 3, v8
	v_mul_lo_u32 v26, v9, s76
	v_pk_fma_f32 v[12:13], v[12:13], 2.0, 1.0 op_sel_hi:[1,0,0] neg_lo:[1,0,0] neg_hi:[1,0,0]
	v_pk_fma_f32 v[10:11], v[10:11], 2.0, 1.0 op_sel_hi:[1,0,0] neg_lo:[1,0,0] neg_hi:[1,0,0]
	v_add3_u32 v14, s74, v24, v26
	v_cvt_pk_bf16_f32 v12, v12, v13
	v_cvt_pk_bf16_f32 v13, v10, v11
	ds_write_b64 v14, v[12:13]
	v_lshlrev_b32_e32 v14, 16, v78
	v_and_b32_e32 v15, 0xffff0000, v78
	v_lshlrev_b32_e32 v18, 16, v80
	v_and_b32_e32 v19, 0xffff0000, v80
	v_lshlrev_b32_e32 v16, 16, v79
	v_and_b32_e32 v17, 0xffff0000, v79
	v_lshlrev_b32_e32 v20, 16, v81
	v_and_b32_e32 v21, 0xffff0000, v81
	v_pk_add_f32 v[14:15], v[18:19], v[14:15]
	v_lshlrev_b32_e32 v18, 16, v76
	v_and_b32_e32 v19, 0xffff0000, v76
	v_pk_add_f32 v[16:17], v[20:21], v[16:17]
	v_lshlrev_b32_e32 v20, 16, v77
	v_and_b32_e32 v21, 0xffff0000, v77
	v_xor_b32_e32 v23, 0x80000000, v19
	v_xor_b32_e32 v22, 0x80000000, v18
	v_pk_fma_f32 v[14:15], v[14:15], 0.5, v[22:23] op_sel_hi:[1,0,1]
	v_xor_b32_e32 v23, 0x80000000, v21
	v_xor_b32_e32 v22, 0x80000000, v20
	v_pk_fma_f32 v[16:17], v[16:17], 0.5, v[22:23] op_sel_hi:[1,0,1]
	v_pk_fma_f32 v[10:11], v[14:15], v[226:227], v[18:19]
	v_pk_fma_f32 v[12:13], v[16:17], v[228:229], v[20:21]
	v_cvt_pk_bf16_f32 v10, v10, v11
	v_cvt_pk_bf16_f32 v11, v12, v13
	v_cndmask_b32_e64 v12, 0, 1, s[36:37]
	v_add3_u32 v24, s75, v24, v26
	v_cmp_ne_u32_e64 s[12:13], 1, v12
	s_andn2_b64 vcc, exec, s[36:37]
	ds_write_b64 v24, v[10:11]
	s_cbranch_vccnz .LBB0_491
	v_lshlrev_b32_e32 v12, 16, v51
	v_lshlrev_b32_e32 v13, 16, v49
	v_lshlrev_b32_e32 v10, 16, v47
	v_add_f32_e32 v12, v12, v13
	v_fma_f32 v12, v12, 0.5, -v10
	v_fmac_f32_e32 v10, v12, v230
	v_mul_f32_e32 v10, 0xbfb8aa3b, v10
	v_exp_f32_e32 v12, v10
	v_add_u32_e32 v10, s46, v9
	v_ashrrev_i32_e32 v11, 31, v10
	v_lshl_add_u64 v[10:11], s[40:41], 0, v[10:11]
	v_add_f32_e32 v9, 1.0, v12
	v_rcp_f32_e32 v9, v9
	v_lshlrev_b64 v[10:11], 8, v[10:11]
	v_lshl_add_u64 v[10:11], s[42:43], 0, v[10:11]
	v_lshlrev_b32_e32 v8, 1, v8
	v_cvt_pk_bf16_f32 v12, v9, s0
	v_mov_b32_e32 v9, v38
	v_lshl_add_u64 v[8:9], v[10:11], 0, v[8:9]
	global_store_short v[8:9], v12, off
; __device__ __forceinline__ void rwkv_chain(LAS unsigned char* lds, int cid, const bf16_t* P0, const float* mu, const float* w0, const float* w2, const float* a0, const float* a2, ...
;     ...
;     RW_ISSUE(dir ? 127 * 32 : 0);
;     ...
;         if (cc + 1 < 128) { RW_IDS const int t0n = dir ? (126 - cc) * 32 : (cc + 1) * 32; RW_ISSUE(t0n); }
.LBB0_491:
	v_readfirstlane_b32 s7, v199
	s_cmp_lg_u32 s7, 0
	s_cbranch_scc1 .Lrw_early_ret
	s_cmpk_eq_i32 s46, 0xfe0
	s_waitcnt lgkmcnt(0)
	s_barrier
	s_cbranch_scc1 .LBB0_512
	s_add_i32 s7, s46, 32
	s_and_b64 s[14:15], s[10:11], exec
	s_cselect_b32 s7, s6, s7
	s_mul_i32 s14, s7, 0xe00
	s_ashr_i32 s15, s14, 31
	s_lshl_b64 s[14:15], s[14:15], 1
	s_add_u32 s16, s88, s14
	s_addc_u32 s17, s89, s15
	v_lshl_add_u64 v[8:9], s[16:17], 0, v[40:41]
	v_mov_b32_e32 v14, v200
	v_lshl_add_u64 v[10:11], v[8:9], 0, s[24:25]
	s_cmp_eq_u32 s7, 0
	s_cbranch_scc1 .Lrw_pf_slow
	s_cmpk_eq_i32 s7, 0xfe0
	s_cbranch_scc1 .Lrw_pf_slow
	v_readfirstlane_b32 s50, v200
	s_cmpk_lt_u32 s50, 0x100
	s_cbranch_scc1 .LBB0_512
	s_mov_b32 s52, 0xffffe400
	s_mov_b32 s53, -1
	s_mov_b64 s[50:51], 0x1c00
	s_mov_b64 s[54:55], 0x2000
	s_mov_b32 s48, 0xfffe4000
	s_mov_b32 s49, -1
	global_load_dwordx2 v[52:53], v[10:11], off
	global_load_dwordx2 v[58:59], v[10:11], off offset:1024
	global_load_dwordx2 v[64:65], v[10:11], off offset:2048
	global_load_dwordx2 v[70:71], v[8:9], off offset:3072
	global_load_dwordx2 v[76:77], v[8:9], off offset:3200
	v_lshl_add_u64 v[12:13], v[10:11], 0, s[52:53]
	v_lshl_add_u64 v[16:17], v[10:11], 0, s[50:51]
	v_lshl_add_u64 v[18:19], v[8:9], 0, s[54:55]
	global_load_dwordx2 v[56:57], v[12:13], off
	global_load_dwordx2 v[60:61], v[12:13], off offset:1024
	global_load_dwordx2 v[66:67], v[12:13], off offset:2048
	global_load_dwordx2 v[72:73], v[8:9], off offset:-4096
	global_load_dwordx2 v[78:79], v[8:9], off offset:-3968
	global_load_dwordx2 v[54:55], v[16:17], off
	global_load_dwordx2 v[62:63], v[16:17], off offset:1024
	global_load_dwordx2 v[68:69], v[16:17], off offset:2048
	global_load_dwordx2 v[74:75], v[18:19], off offset:2048
	global_load_dwordx2 v[80:81], v[18:19], off offset:2176
	v_lshl_add_u64 v[20:21], v[8:9], 0, s[48:49]
	v_lshl_add_u64 v[22:23], v[10:11], 0, s[48:49]
	global_load_dwordx2 v[148:149], v[22:23], off
	global_load_dwordx2 v[154:155], v[22:23], off offset:1024
	global_load_dwordx2 v[160:161], v[22:23], off offset:2048
	global_load_dwordx2 v[166:167], v[20:21], off offset:3072
	global_load_dwordx2 v[172:173], v[20:21], off offset:3200
	v_lshl_add_u64 v[12:13], v[22:23], 0, s[52:53]
	v_lshl_add_u64 v[16:17], v[22:23], 0, s[50:51]
	v_lshl_add_u64 v[18:19], v[20:21], 0, s[54:55]
	global_load_dwordx2 v[152:153], v[12:13], off
	global_load_dwordx2 v[156:157], v[12:13], off offset:1024
	global_load_dwordx2 v[162:163], v[12:13], off offset:2048
	global_load_dwordx2 v[168:169], v[20:21], off offset:-4096
	global_load_dwordx2 v[174:175], v[20:21], off offset:-3968
	global_load_dwordx2 v[150:151], v[16:17], off
	global_load_dwordx2 v[158:159], v[16:17], off offset:1024
	global_load_dwordx2 v[164:165], v[16:17], off offset:2048
	global_load_dwordx2 v[170:171], v[18:19], off offset:2048
	global_load_dwordx2 v[176:177], v[18:19], off offset:2176
	s_and_b64 vcc, exec, s[36:37]
	s_cbranch_vccz .LBB0_512
	v_and_b32_e32 v12, 15, v14
	v_mul_u32_u24_e32 v12, 6, v12
	v_sub_co_u32_e32 v16, vcc, v8, v12
	v_mov_b32_e32 v13, 0
	s_nop 0
	v_subb_co_u32_e32 v17, vcc, v9, v13, vcc
	v_lshl_add_u64 v[16:17], s[38:39], 1, v[16:17]
	v_lshl_add_u64 v[18:19], v[16:17], 0, s[54:55]
	global_load_ushort v47, v[16:17], off offset:3328
	global_load_ushort v51, v[16:17], off offset:-3840
	global_load_ushort v49, v[18:19], off offset:2304
	v_lshl_add_u64 v[16:17], v[16:17], 0, s[48:49]
	v_lshl_add_u64 v[18:19], v[18:19], 0, s[48:49]
	global_load_ushort v178, v[16:17], off offset:3328
	global_load_ushort v179, v[16:17], off offset:-3840
	global_load_ushort v180, v[18:19], off offset:2304
	s_branch .LBB0_512
.Lrw_pf_slow:
	global_load_dwordx2 v[52:53], v[10:11], off
	s_cmp_eq_u32 s7, 0
	s_cselect_b64 s[14:15], -1, 0
	v_cmp_gt_i32_e32 vcc, 16, v14
	s_and_b64 s[14:15], s[14:15], vcc
	v_mov_b32_e32 v54, v38
	v_mov_b32_e32 v55, v38
	s_xor_b64 s[50:51], s[14:15], -1
	v_mov_b64_e32 v[56:57], v[54:55]
	s_and_saveexec_b64 s[48:49], s[50:51]
	s_cbranch_execz .LBB0_494
	v_add_co_u32_e32 v12, vcc, 0xfffff000, v10
	s_nop 1
	v_addc_co_u32_e32 v13, vcc, -1, v11, vcc
	global_load_dwordx2 v[56:57], v[12:13], off offset:-3072

; #define LAS __attribute__((address_space(3)))
; __device__ __forceinline__ unsigned pk2(float lo, float hi) { const f32x2 v = {lo, hi}; return __builtin_bit_cast(unsigned, __builtin_convertvector(v, bf16x2_t)); }
; __device__ __forceinline__ unsigned f2bf(float f) { return pk2(f, 0.f) & 0xffffu; }
; __device__ __forceinline__ float frcp(float x) { return __builtin_amdgcn_rcpf(x); }
; __device__ __forceinline__ void rwkv_chain(LAS unsigned char* lds, int cid, const bf16_t* P0, const float* mu, const float* w0, const float* w2, const float* a0, const float* a2, ...
;     ...
;     for (int cc = 0; cc < 128; ++cc) {
;         const int t0 = dir ? (127 - cc) * 32 : cc * 32;
;         { RW_IDS
;         { const int tok = tid >> 4, c4 = (tid & 15) * 4;
; #pragma unroll
;         for (int i = 0; i < 5; ++i) {
;             const f32x4 mu4 = *(const LAS f32x4*)(cst + (5 + i) * 64 + c4);
;             const f32x4 cv = (f32x4){bflo(rc[i].x), bfhi(rc[i].x), bflo(rc[i].y), bfhi(rc[i].y)};
;             const f32x4 pv = (f32x4){bflo(rpv[i].x), bfhi(rpv[i].x), bflo(rpv[i].y), bfhi(rpv[i].y)}, nv = (f32x4){bflo(rnx[i].x), bfhi(rnx[i].x), bflo(rnx[i].y), bfhi(rnx[i].y)};
;             const f32x4 xv = cv + mu4 * ((pv + nv) * 0.5f - cv);
;             if (i == 0) *(LAS f32x4*)(rS + tok * 64 + c4) = xv;
;             else if (i == 1) *(LAS f32x4*)(kS + tok * 64 + c4) = xv;
;             else if (i == 2) *(LAS f32x4*)(vS + tok * 64 + c4) = xv;
;             else if (i == 3) { float th[4];
; #pragma unroll
;                 for (int e = 0; e < 4; ++e) { const float ex = __expf(2.f * xv[e]); th[e] = 1.f - 2.f * frcp(ex + 1.f); }
;                 u32x2 w; w.x = pk2(th[0], th[1]); w.y = pk2(th[2], th[3]); *(LAS u32x2*)(wdB + tok * 72 + c4) = w; }
;             else { u32x2 w; w.x = pk2(xv[0], xv[1]); w.y = pk2(xv[2], xv[3]); *(LAS u32x2*)(adB + tok * 72 + c4) = w; }
;         } }
;         if (dir == 0) {
;             const int tok = tid >> 4, c = tid & 15, t = t0 + tok;
;             const float cur = bf2f(gcv), prv = bf2f(gpv), nxt = bf2f(gnv);
;             const float x = cur + cst[10 * 64 + c] * (0.5f * (prv + nxt) - cur);
;             SG[((size_t)b * SEQ + t) * 128 + h * 16 + c] = (bf16_t)f2bf(sigmoidf_(x));
;         } }
;         __syncthreads();
;         if (cc + 1 < 128) { RW_IDS const int t0n = dir ? (126 - cc) * 32 : (cc + 1) * 32; RW_ISSUE(t0n); }
.Lrw_early_s0:
	s_cmpk_eq_i32 s46, 0xfe0
	s_cbranch_scc1 .LBB0_488
	s_add_i32 s7, s46, 32
	s_and_b64 vcc, s[10:11], exec
	s_cselect_b32 s7, s6, s7
	s_cmp_eq_u32 s7, 0
	s_cbranch_scc1 .LBB0_488
	s_cmpk_eq_i32 s7, 0xfe0
	s_cbranch_scc1 .LBB0_488
	v_mov_b32_e32 v190, v8
	v_mov_b32_e32 v191, v9
	v_mov_b32_e32 v192, v10
	v_mov_b32_e32 v193, v11
	v_mov_b32_e32 v199, 2
	s_add_i32 s46, s46, 32
	v_mov_b32_e32 v8, v200
	s_waitcnt vmcnt(0)
	s_branch .Lrw_s0_body
.Lrw_early_ret:
	s_cmp_eq_u32 s7, 2
	s_cbranch_scc0 .Lrw_early_done
	v_mov_b64_e32 v[52:53], v[148:149]
	v_mov_b64_e32 v[54:55], v[150:151]
	v_mov_b64_e32 v[56:57], v[152:153]
	v_mov_b64_e32 v[58:59], v[154:155]
	v_mov_b64_e32 v[60:61], v[156:157]
	v_mov_b64_e32 v[62:63], v[158:159]
	v_mov_b64_e32 v[64:65], v[160:161]
	v_mov_b64_e32 v[66:67], v[162:163]
	v_mov_b64_e32 v[68:69], v[164:165]
	v_mov_b64_e32 v[70:71], v[166:167]
	v_mov_b64_e32 v[72:73], v[168:169]
	v_mov_b64_e32 v[74:75], v[170:171]
	v_mov_b64_e32 v[76:77], v[172:173]
	v_mov_b64_e32 v[78:79], v[174:175]
	v_mov_b64_e32 v[80:81], v[176:177]
	v_mov_b32_e32 v47, v178
	v_mov_b32_e32 v51, v179
	v_mov_b32_e32 v49, v180
	v_mov_b32_e32 v199, 1
	v_add_u32_e32 v8, 0xffffff00, v200
	s_branch .Lrw_s0_body
.Lrw_early_done:
	s_sub_i32 s46, s46, 32
	v_mov_b32_e32 v8, v190
	v_mov_b32_e32 v9, v191
	v_mov_b32_e32 v10, v192
	v_mov_b32_e32 v11, v193
	s_branch .LBB0_488
.Lrw_s0_skip:
	s_not_b64 s[12:13], s[36:37]
	s_branch .LBB0_491
